# grid-barrier poll loops back off with s_sleep 3 instead of s_sleep 1 (fewer polls from idle blocks in round tails)
# speedup vs baseline: 1.0031x; 1.0012x over previous
.LBB0_210:
	global_load_dword v15, v16, s[8:9] sc1
	s_waitcnt lgkmcnt(0)
	global_load_dword v0, v16, s[10:11] sc1
	global_load_dword v1, v16, s[12:13] sc1
	global_load_dword v2, v16, s[14:15] sc1
	global_load_dword v3, v16, s[20:21] sc1
	global_load_dword v4, v16, s[28:29] sc1
	global_load_dword v5, v16, s[36:37] sc1
	global_load_dword v6, v16, s[38:39] sc1
	global_load_dword v7, v16, s[40:41] sc1
	global_load_dword v8, v16, s[42:43] sc1
	global_load_dword v9, v16, s[44:45] sc1
	global_load_dword v10, v16, s[46:47] sc1
	global_load_dword v11, v16, s[48:49] sc1
	global_load_dword v12, v16, s[50:51] sc1
	global_load_dword v13, v16, s[52:53] sc1
	global_load_dword v14, v16, s[54:55] sc1
	s_mov_b64 s[56:57], -1
	s_mov_b64 s[58:59], -1
	s_waitcnt vmcnt(14)
	v_add_u32_e32 v17, v0, v15
	s_waitcnt vmcnt(13)
	v_add_u32_e32 v17, v17, v1
	s_waitcnt vmcnt(12)
	v_add_u32_e32 v17, v17, v2
	s_waitcnt vmcnt(11)
	v_add_u32_e32 v17, v17, v3
	s_waitcnt vmcnt(10)
	v_add_u32_e32 v17, v17, v4
	s_waitcnt vmcnt(9)
	v_add_u32_e32 v17, v17, v5
	s_waitcnt vmcnt(8)
	v_add_u32_e32 v17, v17, v6
	s_waitcnt vmcnt(7)
	v_add_u32_e32 v17, v17, v7
	s_waitcnt vmcnt(6)
	v_add_u32_e32 v17, v17, v8
	s_waitcnt vmcnt(5)
	v_add_u32_e32 v17, v17, v9
	s_waitcnt vmcnt(4)
	v_add_u32_e32 v17, v17, v10
	s_waitcnt vmcnt(3)
	v_add_u32_e32 v17, v17, v11
	s_waitcnt vmcnt(2)
	v_add_u32_e32 v17, v17, v12
	s_waitcnt vmcnt(1)
	v_add_u32_e32 v17, v17, v13
	s_waitcnt vmcnt(0)
	v_add_u32_e32 v17, v17, v14
	v_cmp_eq_u32_e32 vcc, s3, v17
	s_cbranch_vccnz .LBB0_209
	s_and_b32 s56, s62, 0xff
	s_cmp_eq_u32 s56, 0
	s_mov_b64 s[56:57], -1
	s_mov_b64 s[60:61], -1
	s_sleep 3
	s_cbranch_scc1 .LBB0_214
	s_and_b64 vcc, exec, s[60:61]
	s_cbranch_vccz .LBB0_209

.LBB0_228:
	s_and_b32 s38, s3, 0xff
	s_mov_b64 s[36:37], -1
	s_cmp_lg_u32 s38, 0
	s_mov_b64 s[40:41], -1
	s_sleep 3
	s_cbranch_scc0 .LBB0_231
	s_and_b64 vcc, exec, s[40:41]
	s_cbranch_vccz .LBB0_227

.LBB0_245:
	s_and_b32 s36, s3, 0xff
	s_cmp_lg_u32 s36, 0
	s_mov_b64 s[38:39], -1
	s_sleep 3
	s_cbranch_scc0 .LBB0_248
	s_mov_b64 s[40:41], -1
	s_and_b64 vcc, exec, s[38:39]
	s_cbranch_vccz .LBB0_244

.LBB0_355:
	global_load_dword v15, v16, s[10:11] sc1
	s_waitcnt lgkmcnt(0)
	global_load_dword v0, v16, s[20:21] sc1
	global_load_dword v1, v16, s[28:29] sc1
	global_load_dword v2, v16, s[36:37] sc1
	global_load_dword v3, v16, s[38:39] sc1
	global_load_dword v4, v16, s[40:41] sc1
	global_load_dword v5, v16, s[42:43] sc1
	global_load_dword v6, v16, s[44:45] sc1
	global_load_dword v7, v16, s[46:47] sc1
	global_load_dword v8, v16, s[48:49] sc1
	global_load_dword v9, v16, s[50:51] sc1
	global_load_dword v10, v16, s[52:53] sc1
	global_load_dword v11, v16, s[54:55] sc1
	global_load_dword v12, v16, s[56:57] sc1
	global_load_dword v13, v16, s[58:59] sc1
	global_load_dword v14, v16, s[60:61] sc1
	s_mov_b64 s[62:63], -1
	s_mov_b64 s[64:65], -1
	s_waitcnt vmcnt(14)
	v_add_u32_e32 v17, v0, v15
	s_waitcnt vmcnt(13)
	v_add_u32_e32 v17, v17, v1
	s_waitcnt vmcnt(12)
	v_add_u32_e32 v17, v17, v2
	s_waitcnt vmcnt(11)
	v_add_u32_e32 v17, v17, v3
	s_waitcnt vmcnt(10)
	v_add_u32_e32 v17, v17, v4
	s_waitcnt vmcnt(9)
	v_add_u32_e32 v17, v17, v5
	s_waitcnt vmcnt(8)
	v_add_u32_e32 v17, v17, v6
	s_waitcnt vmcnt(7)
	v_add_u32_e32 v17, v17, v7
	s_waitcnt vmcnt(6)
	v_add_u32_e32 v17, v17, v8
	s_waitcnt vmcnt(5)
	v_add_u32_e32 v17, v17, v9
	s_waitcnt vmcnt(4)
	v_add_u32_e32 v17, v17, v10
	s_waitcnt vmcnt(3)
	v_add_u32_e32 v17, v17, v11
	s_waitcnt vmcnt(2)
	v_add_u32_e32 v17, v17, v12
	s_waitcnt vmcnt(1)
	v_add_u32_e32 v17, v17, v13
	s_waitcnt vmcnt(0)
	v_add_u32_e32 v17, v17, v14
	v_cmp_eq_u32_e32 vcc, s3, v17
	s_cbranch_vccnz .LBB0_354
	s_and_b32 s62, s68, 0xff
	s_cmp_eq_u32 s62, 0
	s_mov_b64 s[62:63], -1
	s_mov_b64 s[66:67], -1
	s_sleep 3
	s_cbranch_scc1 .LBB0_359
	s_and_b64 vcc, exec, s[66:67]
	s_cbranch_vccz .LBB0_354

.LBB0_373:
	s_and_b32 s44, s3, 0xff
	s_mov_b64 s[42:43], -1
	s_cmp_lg_u32 s44, 0
	s_mov_b64 s[46:47], -1
	s_sleep 3
	s_cbranch_scc0 .LBB0_376
	s_and_b64 vcc, exec, s[46:47]
	s_cbranch_vccz .LBB0_372

.LBB0_390:
	s_and_b32 s42, s3, 0xff
	s_cmp_lg_u32 s42, 0
	s_mov_b64 s[44:45], -1
	s_sleep 3
	s_cbranch_scc0 .LBB0_393
	s_mov_b64 s[46:47], -1
	s_and_b64 vcc, exec, s[44:45]
	s_cbranch_vccz .LBB0_389

.LBB0_486:
	global_load_dword v15, v16, s[8:9] sc1
	s_waitcnt lgkmcnt(0)
	global_load_dword v0, v16, s[10:11] sc1
	global_load_dword v1, v16, s[20:21] sc1
	global_load_dword v2, v16, s[28:29] sc1
	global_load_dword v3, v16, s[36:37] sc1
	global_load_dword v4, v16, s[38:39] sc1
	global_load_dword v5, v16, s[40:41] sc1
	global_load_dword v6, v16, s[42:43] sc1
	global_load_dword v7, v16, s[44:45] sc1
	global_load_dword v8, v16, s[46:47] sc1
	global_load_dword v9, v16, s[48:49] sc1
	global_load_dword v10, v16, s[50:51] sc1
	global_load_dword v11, v16, s[52:53] sc1
	global_load_dword v12, v16, s[54:55] sc1
	global_load_dword v13, v16, s[56:57] sc1
	global_load_dword v14, v16, s[58:59] sc1
	s_mov_b64 s[60:61], -1
	s_mov_b64 s[62:63], -1
	s_waitcnt vmcnt(14)
	v_add_u32_e32 v17, v0, v15
	s_waitcnt vmcnt(13)
	v_add_u32_e32 v17, v17, v1
	s_waitcnt vmcnt(12)
	v_add_u32_e32 v17, v17, v2
	s_waitcnt vmcnt(11)
	v_add_u32_e32 v17, v17, v3
	s_waitcnt vmcnt(10)
	v_add_u32_e32 v17, v17, v4
	s_waitcnt vmcnt(9)
	v_add_u32_e32 v17, v17, v5
	s_waitcnt vmcnt(8)
	v_add_u32_e32 v17, v17, v6
	s_waitcnt vmcnt(7)
	v_add_u32_e32 v17, v17, v7
	s_waitcnt vmcnt(6)
	v_add_u32_e32 v17, v17, v8
	s_waitcnt vmcnt(5)
	v_add_u32_e32 v17, v17, v9
	s_waitcnt vmcnt(4)
	v_add_u32_e32 v17, v17, v10
	s_waitcnt vmcnt(3)
	v_add_u32_e32 v17, v17, v11
	s_waitcnt vmcnt(2)
	v_add_u32_e32 v17, v17, v12
	s_waitcnt vmcnt(1)
	v_add_u32_e32 v17, v17, v13
	s_waitcnt vmcnt(0)
	v_add_u32_e32 v17, v17, v14
	v_cmp_eq_u32_e32 vcc, s3, v17
	s_cbranch_vccnz .LBB0_485
	s_and_b32 s60, s66, 0xff
	s_cmp_eq_u32 s60, 0
	s_mov_b64 s[60:61], -1
	s_mov_b64 s[64:65], -1
	s_sleep 3
	s_cbranch_scc1 .LBB0_490
	s_and_b64 vcc, exec, s[64:65]
	s_cbranch_vccz .LBB0_485

.LBB0_504:
	s_and_b32 s42, s3, 0xff
	s_mov_b64 s[40:41], -1
	s_cmp_lg_u32 s42, 0
	s_mov_b64 s[44:45], -1
	s_sleep 3
	s_cbranch_scc0 .LBB0_507
	s_and_b64 vcc, exec, s[44:45]
	s_cbranch_vccz .LBB0_503

.LBB0_521:
	s_and_b32 s40, s3, 0xff
	s_cmp_lg_u32 s40, 0
	s_mov_b64 s[42:43], -1
	s_sleep 3
	s_cbranch_scc0 .LBB0_524
	s_mov_b64 s[44:45], -1
	s_and_b64 vcc, exec, s[42:43]
	s_cbranch_vccz .LBB0_520

.LBB0_751:
	global_load_dword v15, v16, s[6:7] sc1
	s_waitcnt lgkmcnt(0)
	global_load_dword v0, v16, s[8:9] sc1
	global_load_dword v1, v16, s[10:11] sc1
	global_load_dword v2, v16, s[20:21] sc1
	global_load_dword v3, v16, s[28:29] sc1
	global_load_dword v4, v16, s[36:37] sc1
	global_load_dword v5, v16, s[38:39] sc1
	global_load_dword v6, v16, s[40:41] sc1
	global_load_dword v7, v16, s[42:43] sc1
	global_load_dword v8, v16, s[44:45] sc1
	global_load_dword v9, v16, s[46:47] sc1
	global_load_dword v10, v16, s[48:49] sc1
	global_load_dword v11, v16, s[50:51] sc1
	global_load_dword v12, v16, s[52:53] sc1
	global_load_dword v13, v16, s[54:55] sc1
	global_load_dword v14, v16, s[56:57] sc1
	s_mov_b64 s[58:59], -1
	s_mov_b64 s[60:61], -1
	s_waitcnt vmcnt(14)
	v_add_u32_e32 v17, v0, v15
	s_waitcnt vmcnt(13)
	v_add_u32_e32 v17, v17, v1
	s_waitcnt vmcnt(12)
	v_add_u32_e32 v17, v17, v2
	s_waitcnt vmcnt(11)
	v_add_u32_e32 v17, v17, v3
	s_waitcnt vmcnt(10)
	v_add_u32_e32 v17, v17, v4
	s_waitcnt vmcnt(9)
	v_add_u32_e32 v17, v17, v5
	s_waitcnt vmcnt(8)
	v_add_u32_e32 v17, v17, v6
	s_waitcnt vmcnt(7)
	v_add_u32_e32 v17, v17, v7
	s_waitcnt vmcnt(6)
	v_add_u32_e32 v17, v17, v8
	s_waitcnt vmcnt(5)
	v_add_u32_e32 v17, v17, v9
	s_waitcnt vmcnt(4)
	v_add_u32_e32 v17, v17, v10
	s_waitcnt vmcnt(3)
	v_add_u32_e32 v17, v17, v11
	s_waitcnt vmcnt(2)
	v_add_u32_e32 v17, v17, v12
	s_waitcnt vmcnt(1)
	v_add_u32_e32 v17, v17, v13
	s_waitcnt vmcnt(0)
	v_add_u32_e32 v17, v17, v14
	v_cmp_eq_u32_e32 vcc, s3, v17
	s_cbranch_vccnz .LBB0_750
	s_and_b32 s58, s64, 0xff
	s_cmp_eq_u32 s58, 0
	s_mov_b64 s[58:59], -1
	s_mov_b64 s[62:63], -1
	s_sleep 3
	s_cbranch_scc1 .LBB0_755
	s_and_b64 vcc, exec, s[62:63]
	s_cbranch_vccz .LBB0_750

.LBB0_769:
	s_and_b32 s40, s3, 0xff
	s_mov_b64 s[38:39], -1
	s_cmp_lg_u32 s40, 0
	s_mov_b64 s[42:43], -1
	s_sleep 3
	s_cbranch_scc0 .LBB0_772
	s_and_b64 vcc, exec, s[42:43]
	s_cbranch_vccz .LBB0_768

.LBB0_786:
	s_and_b32 s38, s3, 0xff
	s_cmp_lg_u32 s38, 0
	s_mov_b64 s[40:41], -1
	s_sleep 3
	s_cbranch_scc0 .LBB0_789
	s_mov_b64 s[42:43], -1
	s_and_b64 vcc, exec, s[40:41]
	s_cbranch_vccz .LBB0_785

.LBB0_1047:
	global_load_dword v15, v16, s[8:9] sc1
	s_waitcnt lgkmcnt(0)
	global_load_dword v0, v16, s[10:11] sc1
	global_load_dword v1, v16, s[16:17] sc1
	global_load_dword v2, v16, s[18:19] sc1
	global_load_dword v3, v16, s[20:21] sc1
	global_load_dword v4, v16, s[28:29] sc1
	global_load_dword v5, v16, s[36:37] sc1
	global_load_dword v6, v16, s[38:39] sc1
	global_load_dword v7, v16, s[40:41] sc1
	global_load_dword v8, v16, s[42:43] sc1
	global_load_dword v9, v16, s[44:45] sc1
	global_load_dword v10, v16, s[46:47] sc1
	global_load_dword v11, v16, s[48:49] sc1
	global_load_dword v12, v16, s[50:51] sc1
	global_load_dword v13, v16, s[52:53] sc1
	global_load_dword v14, v16, s[54:55] sc1
	s_mov_b64 s[56:57], -1
	s_mov_b64 s[58:59], -1
	s_waitcnt vmcnt(14)
	v_add_u32_e32 v17, v0, v15
	s_waitcnt vmcnt(13)
	v_add_u32_e32 v17, v17, v1
	s_waitcnt vmcnt(12)
	v_add_u32_e32 v17, v17, v2
	s_waitcnt vmcnt(11)
	v_add_u32_e32 v17, v17, v3
	s_waitcnt vmcnt(10)
	v_add_u32_e32 v17, v17, v4
	s_waitcnt vmcnt(9)
	v_add_u32_e32 v17, v17, v5
	s_waitcnt vmcnt(8)
	v_add_u32_e32 v17, v17, v6
	s_waitcnt vmcnt(7)
	v_add_u32_e32 v17, v17, v7
	s_waitcnt vmcnt(6)
	v_add_u32_e32 v17, v17, v8
	s_waitcnt vmcnt(5)
	v_add_u32_e32 v17, v17, v9
	s_waitcnt vmcnt(4)
	v_add_u32_e32 v17, v17, v10
	s_waitcnt vmcnt(3)
	v_add_u32_e32 v17, v17, v11
	s_waitcnt vmcnt(2)
	v_add_u32_e32 v17, v17, v12
	s_waitcnt vmcnt(1)
	v_add_u32_e32 v17, v17, v13
	s_waitcnt vmcnt(0)
	v_add_u32_e32 v17, v17, v14
	v_cmp_eq_u32_e32 vcc, s3, v17
	s_cbranch_vccnz .LBB0_1046
	s_and_b32 s56, s62, 0xff
	s_cmp_eq_u32 s56, 0
	s_mov_b64 s[56:57], -1
	s_mov_b64 s[60:61], -1
	s_sleep 3
	s_cbranch_scc1 .LBB0_1051
	s_and_b64 vcc, exec, s[60:61]
	s_cbranch_vccz .LBB0_1046

.LBB0_1132:
	global_load_dword v15, v16, s[8:9] sc1
	s_waitcnt lgkmcnt(0)
	global_load_dword v0, v16, s[10:11] sc1
	global_load_dword v1, v16, s[16:17] sc1
	global_load_dword v2, v16, s[18:19] sc1
	global_load_dword v3, v16, s[20:21] sc1
	global_load_dword v4, v16, s[28:29] sc1
	global_load_dword v5, v16, s[36:37] sc1
	global_load_dword v6, v16, s[38:39] sc1
	global_load_dword v7, v16, s[40:41] sc1
	global_load_dword v8, v16, s[42:43] sc1
	global_load_dword v9, v16, s[44:45] sc1
	global_load_dword v10, v16, s[46:47] sc1
	global_load_dword v11, v16, s[48:49] sc1
	global_load_dword v12, v16, s[50:51] sc1
	global_load_dword v13, v16, s[52:53] sc1
	global_load_dword v14, v16, s[54:55] sc1
	s_mov_b64 s[56:57], -1
	s_mov_b64 s[58:59], -1
	s_waitcnt vmcnt(14)
	v_add_u32_e32 v17, v0, v15
	s_waitcnt vmcnt(13)
	v_add_u32_e32 v17, v17, v1
	s_waitcnt vmcnt(12)
	v_add_u32_e32 v17, v17, v2
	s_waitcnt vmcnt(11)
	v_add_u32_e32 v17, v17, v3
	s_waitcnt vmcnt(10)
	v_add_u32_e32 v17, v17, v4
	s_waitcnt vmcnt(9)
	v_add_u32_e32 v17, v17, v5
	s_waitcnt vmcnt(8)
	v_add_u32_e32 v17, v17, v6
	s_waitcnt vmcnt(7)
	v_add_u32_e32 v17, v17, v7
	s_waitcnt vmcnt(6)
	v_add_u32_e32 v17, v17, v8
	s_waitcnt vmcnt(5)
	v_add_u32_e32 v17, v17, v9
	s_waitcnt vmcnt(4)
	v_add_u32_e32 v17, v17, v10
	s_waitcnt vmcnt(3)
	v_add_u32_e32 v17, v17, v11
	s_waitcnt vmcnt(2)
	v_add_u32_e32 v17, v17, v12
	s_waitcnt vmcnt(1)
	v_add_u32_e32 v17, v17, v13
	s_waitcnt vmcnt(0)
	v_add_u32_e32 v17, v17, v14
	v_cmp_eq_u32_e32 vcc, s3, v17
	s_cbranch_vccnz .LBB0_1131
	s_and_b32 s35, s31, 0xff
	s_cmp_eq_u32 s35, 0
	s_mov_b64 s[60:61], -1
	s_sleep 3
	s_cbranch_scc1 .LBB0_1136
	s_and_b64 vcc, exec, s[60:61]
	s_cbranch_vccz .LBB0_1131

.LBB0_1150:
	s_and_b32 s31, s3, 0xff
	s_mov_b64 s[36:37], -1
	s_cmp_lg_u32 s31, 0
	s_mov_b64 s[40:41], -1
	s_sleep 3
	s_cbranch_scc0 .LBB0_1153
	s_and_b64 vcc, exec, s[40:41]
	s_cbranch_vccz .LBB0_1149

.LBB0_1167:
	s_and_b32 s31, s3, 0xff
	s_cmp_lg_u32 s31, 0
	s_mov_b64 s[38:39], -1
	s_sleep 3
	s_cbranch_scc0 .LBB0_1170
	s_mov_b64 s[40:41], -1
	s_and_b64 vcc, exec, s[38:39]
	s_cbranch_vccz .LBB0_1166
